# same as previous best (scan rewrite, cprep hoist, EpiIn loads, attention LDS pipelining, carry batching) plus 40 B of dead padding so the later GEMM loops keep their baseline 64-byte phase
# speedup vs baseline: 1.0068x; 1.0068x over previous
; #define PG8_STAGE(bufoff, gbase, voff) do { _Pragma("unroll") for (int _i = 0; _i < 2; ++_i) \
;         __builtin_amdgcn_global_load_lds((const unsigned*)((const char*)(gbase) + (voff)[_i]), (LAS unsigned*)(lds + (bufoff) + ldsw + _i * 8192), 16, 0, 0); } while (0)
; #define PG8_WAIT_V(n) asm volatile("s_waitcnt vmcnt(" #n ")" ::: "memory")
; #define PG8_BAR __builtin_amdgcn_s_barrier()
;     ...
;     const int aoff = lds_byte(wr * 64 + fr, fq * 8), boff = lds_byte(wc * 32 + fr, fq * 8);
;     ...
;         PG8_STAGE(PG8_SB(0, 0), cB, voffB); PG8_STAGE(PG8_SA(0, 0), cA, voffA); PG8_STAGE(PG8_SA(0, 1), cA + hstep, voffA);
;         if (wr == 1) PG8_BAR;
;         PG8_WAIT_V(2); PG8_BAR;
;         PG8_STAGE(PG8_SB(1, 0), cB + kstep, voffB); PG8_STAGE(PG8_SA(1, 0), cA + kstep, voffA);
;         PG8_WAIT_V(4); PG8_BAR;
.LBB0_1362:
	v_lshl_add_u64 v[4:5], s[44:45], 0, v[34:35]
	v_mov_b32_e32 v97, v35
	v_lshl_add_u64 v[6:7], s[44:45], 0, v[96:97]
	v_mov_b32_e32 v101, v35
	s_add_i32 m0, s28, 0x18000
	v_lshl_add_u64 v[4:5], v[4:5], 0, s[22:23]
	v_lshl_add_u64 v[8:9], s[38:39], 0, v[100:101]
	v_mov_b32_e32 v99, v35
	s_waitcnt vmcnt(2)
	s_barrier
	global_load_lds_dwordx4 v[4:5], off
	v_lshl_add_u64 v[4:5], v[6:7], 0, s[22:23]
	s_add_i32 m0, s28, 0x1a000
	s_add_i32 s33, s28, 0x8000
	v_lshl_add_u64 v[10:11], s[38:39], 0, v[98:99]
	global_load_lds_dwordx4 v[4:5], off
	v_lshl_add_u64 v[4:5], v[8:9], 0, s[22:23]
	s_mov_b32 m0, s33
	s_add_i32 s46, s28, 0xa000
	global_load_lds_dwordx4 v[4:5], off
	v_lshl_add_u64 v[4:5], v[10:11], 0, s[22:23]
	s_mov_b32 m0, s46
	v_and_b32_e32 v3, 15, v2
	global_load_lds_dwordx4 v[4:5], off
	v_lshrrev_b32_e32 v4, 1, v2
	v_and_b32_e32 v4, 24, v4
	v_lshlrev_b32_e32 v5, 1, v4
	v_lshlrev_b32_e32 v2, 2, v2
	s_lshl_b32 s1, s1, 5
	v_lshl_or_b32 v200, s4, 6, v3
	v_lshl_or_b32 v3, v3, 6, v5
	s_lshl_b32 s4, s4, 13
	v_and_b32_e32 v2, 32, v2
	s_and_b32 s1, s1, 0x60
	v_bitop3_b32 v5, v3, s4, v2 bitop3:0xde
	s_lshl_b32 s4, s1, 7
	s_waitcnt vmcnt(4)
	s_cmpk_lt_u32 s0, 0x100
	v_or_b32_e32 v203, s1, v4
	v_readlane_b32 s0, v253, 9
	s_mov_b32 s47, 1
	v_bitop3_b32 v201, v3, s4, v2 bitop3:0xde
	v_add_u32_e32 v202, 0, v5
	s_cselect_b64 s[16:17], -1, 0
	s_mov_b32 s42, 0
	v_readlane_b32 s43, v253, 3
	s_mov_b32 s48, s0
	s_barrier
	v_readlane_b32 s1, v253, 10
	s_branch .LBB0_1365
	s_nop 0
	s_nop 0
	s_nop 0
	s_nop 0
	s_nop 0
	s_nop 0
	s_nop 0
	s_nop 0
	s_nop 0
	s_nop 0
